# F1: gate loads issued between the two prologue LDS-DMA stages (first counted wait no longer retires them)
# speedup vs baseline: 1.0056x; 1.0056x over previous
.LBB0_162:
	s_cmp_eq_u32 s11, 1
	s_mov_b32 s3, 0x530000
	s_cselect_b32 s0, s88, s82
	s_cselect_b32 s2, s89, s83
	s_cselect_b32 s4, s3, 0x630000
	s_cselect_b32 s12, 16, 8
	s_cselect_b32 s13, 10, 9
	s_cmp_eq_u32 s11, 0
	s_cselect_b32 s3, s81, s2
	s_cselect_b32 s2, s80, s0
	s_cselect_b32 s0, 0x4b0000, s4
	s_lshl_b32 s0, s0, 1
	v_mov_b32_e32 v4, v204
	s_add_u32 s4, s97, s0
	v_readfirstlane_b32 s14, v4
	s_addc_u32 s5, s79, 0
	s_ashr_i32 s15, s14, 6
	v_bfe_u32 v0, v4, 3, 3
	s_and_b32 s16, s15, 1
	v_lshl_or_b32 v5, s15, 3, v0
	v_and_b32_e32 v0, 7, v4
	s_lshl_b32 s0, s16, 2
	v_bfe_u32 v6, v4, 4, 2
	v_bitop3_b32 v7, s0, v0, v6 bitop3:0x36
	v_add_u32_e32 v0, s9, v5
	v_ashrrev_i32_e32 v1, 31, v0
	v_lshlrev_b64 v[2:3], s13, v[0:1]
	v_lshl_add_u64 v[2:3], v[2:3], 1, s[2:3]
	v_lshlrev_b32_e32 v188, 4, v7
	v_lshl_add_u64 v[178:179], v[2:3], 0, v[188:189]
	v_add_u32_e32 v2, 64, v0
	v_ashrrev_i32_e32 v3, 31, v2
	v_lshlrev_b64 v[2:3], s13, v[2:3]
	v_lshl_add_u64 v[2:3], v[2:3], 1, s[2:3]
	v_lshl_add_u64 v[180:181], v[2:3], 0, v[188:189]
	v_add_u32_e32 v2, 0x80, v0
	v_add_u32_e32 v0, 0xc0, v0
	v_ashrrev_i32_e32 v1, 31, v0
	v_lshlrev_b64 v[0:1], s13, v[0:1]
	v_ashrrev_i32_e32 v3, 31, v2
	v_lshl_add_u64 v[0:1], v[0:1], 1, s[2:3]
	v_lshlrev_b64 v[2:3], s13, v[2:3]
	v_lshl_add_u64 v[184:185], v[0:1], 0, v[188:189]
	v_add_u32_e32 v0, s10, v5
	v_lshl_add_u64 v[2:3], v[2:3], 1, s[2:3]
	v_ashrrev_i32_e32 v1, 31, v0
	v_lshl_add_u64 v[182:183], v[2:3], 0, v[188:189]
	v_lshlrev_b64 v[2:3], s13, v[0:1]
	v_add_u32_e32 v0, 64, v0
	v_ashrrev_i32_e32 v1, 31, v0
	s_lshl_b32 s2, s15, 10
	v_lshlrev_b64 v[0:1], s13, v[0:1]
	s_add_i32 s13, s2, 0
	s_mov_b32 m0, s13
	v_lshl_add_u64 v[2:3], v[2:3], 1, s[4:5]
	global_load_lds_dwordx4 v[178:179], off
	s_add_i32 m0, s13, 0x2000
	v_lshl_add_u64 v[186:187], v[2:3], 0, v[188:189]
	global_load_lds_dwordx4 v[180:181], off
	s_add_i32 m0, s13, 0x4000
	v_lshl_add_u64 v[0:1], v[0:1], 1, s[4:5]
	global_load_lds_dwordx4 v[182:183], off
	s_add_i32 m0, s13, 0x6000
	v_lshl_add_u64 v[190:191], v[0:1], 0, v[188:189]
	global_load_lds_dwordx4 v[184:185], off
	s_add_i32 m0, s13, 0x8000
	v_lshl_add_u64 v[0:1], v[178:179], 0, s[92:93]
	global_load_lds_dwordx4 v[186:187], off
	s_add_i32 m0, s13, 0xa000
	s_lshr_b32 s2, s14, 1
	global_load_lds_dwordx4 v[190:191], off
	s_lshl_b32 s0, s11, 11
	s_add_u32 vcc_lo, s94, s0
	s_addc_u32 vcc_hi, s95, 0
	v_lshl_add_u64 v[196:197], vcc, 0, v[94:95]
	v_lshl_add_u64 v[196:197], v[196:197], 0, v[66:67]
	global_load_dwordx2 v[176:177], v[196:197], off
	global_load_dwordx2 v[174:175], v[196:197], off offset:32
	global_load_dwordx2 v[172:173], v[196:197], off offset:64
	global_load_dwordx2 v[170:171], v[196:197], off offset:96
	v_lshl_add_u64 v[196:197], vcc, 0, v[114:115]
	v_lshl_add_u64 v[196:197], v[196:197], 0, v[66:67]
	global_load_dwordx2 v[168:169], v[196:197], off
	global_load_dwordx2 v[166:167], v[196:197], off offset:32
	global_load_dwordx2 v[164:165], v[196:197], off offset:64
	global_load_dwordx2 v[162:163], v[196:197], off offset:96
	v_lshl_add_u64 v[196:197], vcc, 0, v[126:127]
	v_lshl_add_u64 v[196:197], v[196:197], 0, v[66:67]
	global_load_dwordx2 v[160:161], v[196:197], off
	global_load_dwordx2 v[158:159], v[196:197], off offset:32
	global_load_dwordx2 v[156:157], v[196:197], off offset:64
	global_load_dwordx2 v[154:155], v[196:197], off offset:96
	v_lshl_add_u64 v[196:197], vcc, 0, v[128:129]
	v_lshl_add_u64 v[196:197], v[196:197], 0, v[66:67]
	global_load_dwordx2 v[152:153], v[196:197], off
	global_load_dwordx2 v[150:151], v[196:197], off offset:32
	global_load_dwordx2 v[148:149], v[196:197], off offset:64
	global_load_dwordx2 v[146:147], v[196:197], off offset:96
	s_add_i32 m0, s13, 0xc000
	s_and_b32 s2, s2, 0x1ffffc0
	global_load_lds_dwordx4 v[0:1], off
	v_lshl_add_u64 v[0:1], v[180:181], 0, s[92:93]
	s_add_i32 m0, s13, 0xe000
	s_movk_i32 s0, 0x80
	global_load_lds_dwordx4 v[0:1], off
	v_lshl_add_u64 v[0:1], v[182:183], 0, s[92:93]
	s_add_i32 m0, s13, 0x10000
	s_lshl_b32 s14, s16, 13
	global_load_lds_dwordx4 v[0:1], off
	v_lshl_add_u64 v[0:1], v[184:185], 0, s[92:93]
	s_add_i32 m0, s13, 0x12000
	s_mov_b32 s15, 0
	global_load_lds_dwordx4 v[0:1], off
	v_lshl_add_u64 v[0:1], v[186:187], 0, s[92:93]
	s_add_i32 m0, s13, 0x14000
	s_mov_b32 s16, 0
	global_load_lds_dwordx4 v[0:1], off
	v_lshl_add_u64 v[0:1], v[190:191], 0, s[92:93]
	s_add_i32 m0, s13, 0x16000
	v_mov_b32_e32 v2, v192
	global_load_lds_dwordx4 v[0:1], off
	s_waitcnt vmcnt(22)
	v_bfe_u32 v1, v4, 1, 3
	s_waitcnt lgkmcnt(0)
	s_barrier
	v_and_b32_e32 v0, 15, v4
	v_xor_b32_e32 v1, v6, v1
	v_lshlrev_b32_e32 v188, 4, v1
	v_or_b32_e32 v1, s2, v0
	v_lshlrev_b32_e32 v193, 7, v1
	v_lshlrev_b32_e32 v194, 7, v0
	v_xor_b32_e32 v195, 64, v188
	v_mov_b32_e32 v0, 0
	v_mov_b32_e32 v1, v192
	v_mov_b32_e32 v3, v192
	v_mov_b32_e32 v4, 0
	v_mov_b32_e32 v5, v192
	v_mov_b32_e32 v6, v192
	v_mov_b32_e32 v7, v192
	v_mov_b32_e32 v8, 0
	v_mov_b32_e32 v9, v192
	v_mov_b32_e32 v10, v192
	v_mov_b32_e32 v11, v192
	v_mov_b32_e32 v12, 0
	v_mov_b32_e32 v13, v192
	v_mov_b32_e32 v14, v192
	v_mov_b32_e32 v15, v192
	v_mov_b32_e32 v16, 0
	v_mov_b32_e32 v17, v192
	v_mov_b32_e32 v18, v192
	v_mov_b32_e32 v19, v192
	v_mov_b32_e32 v20, 0
	v_mov_b32_e32 v21, v192
	v_mov_b32_e32 v22, v192
	v_mov_b32_e32 v23, v192
	v_mov_b32_e32 v24, 0
	v_mov_b32_e32 v25, v192
	v_mov_b32_e32 v26, v192
	v_mov_b32_e32 v27, v192
	v_mov_b32_e32 v28, 0
	v_mov_b32_e32 v29, v192
	v_mov_b32_e32 v30, v192
	v_mov_b32_e32 v31, v192
	v_mov_b32_e32 v32, 0
	v_mov_b32_e32 v33, v192
	v_mov_b32_e32 v34, v192
	v_mov_b32_e32 v35, v192
	v_mov_b32_e32 v36, 0
	v_mov_b32_e32 v37, v192
	v_mov_b32_e32 v38, v192
	v_mov_b32_e32 v39, v192
	v_mov_b32_e32 v40, 0
	v_mov_b32_e32 v41, v192
	v_mov_b32_e32 v42, v192
	v_mov_b32_e32 v43, v192
	v_mov_b32_e32 v44, 0
	v_mov_b32_e32 v45, v192
	v_mov_b32_e32 v46, v192
	v_mov_b32_e32 v47, v192
	v_mov_b32_e32 v48, 0
	v_mov_b32_e32 v49, v192
	v_mov_b32_e32 v50, v192
	v_mov_b32_e32 v51, v192
	v_mov_b32_e32 v52, 0
	v_mov_b32_e32 v53, v192
	v_mov_b32_e32 v54, v192
	v_mov_b32_e32 v55, v192
	v_mov_b32_e32 v56, 0
	v_mov_b32_e32 v57, v192
	v_mov_b32_e32 v58, v192
	v_mov_b32_e32 v59, v192
	v_mov_b32_e32 v60, 0
	v_mov_b32_e32 v61, v192
	v_mov_b32_e32 v62, v192
	v_mov_b32_e32 v63, v192
	s_branch .LBB0_164
